# attention static priority raise on the other wave half (waves 0-3) for comparison
# speedup vs baseline: 1.0044x; 1.0044x over previous
; #define LAS __attribute__((address_space(3)))
; __device__ __forceinline__ void attn_phase(const Params& p, LAS unsigned char* lds, int li, int tid, int G, bf16_t* __restrict__ dst, const bf16_t* __restrict__ ZGA) {
;     ...
;     auto dma_stage = [&](int item, int kb, int buf) {
;         int l = tid & 63; asm volatile("" : "+v"(l));
;         const int tb = item >> 2, hk = item & 3, tk = tb * 128 + (kb - 1) * 128;
;         LAS unsigned char* kl = lds + buf * 65536; LAS unsigned char* vl = kl + 32768;
; #pragma unroll
;         for (int i = 0; i < 4; ++i) {
;             const int r = 4 * (4 * w + i) + (l >> 4), c = (l & 15) ^ (r & 15);
;             __builtin_amdgcn_global_load_lds((const unsigned*)(ZK + (size_t)(tk + r) * 512 + hk * 128 + c * 8), (LAS unsigned*)(kl + (4 * w + i) * 1024), 16, 0, 0);
;             __builtin_amdgcn_global_load_lds((const unsigned*)(ZVT + (size_t)(hk * 128 + r) * T + tk + c * 8), (LAS unsigned*)(vl + (4 * w + i) * 1024), 16, 0, 0);
;         }
;     };
;     int buf = 0, curhk = -1;
;     int ibase, istep, icnt;
;     if (G & 7) { ibase = blockIdx.x; istep = G; icnt = ibase < 1024 ? (1024 - ibase + G - 1) / G : 0; }
;     else { const int nper = G >> 3, j0 = blockIdx.x >> 3; ibase = (blockIdx.x & 7) * 128 + j0; istep = nper; icnt = j0 < 128 ? (128 - j0 + nper - 1) / nper : 0; }
;     u32x4 qraw[3][4];
;     auto load_q = [&](int item, int lq_, int g_) {
;         const int tb = item >> 2, hk = item & 3;
; #pragma unroll
;         for (int mb = 0; mb < 3; ++mb) {
;             const int hh = mb, r = 16 * w + lq_;
;             const bf16_t* qp = Z0 + (size_t)(tb * 128 + r) * 2048 + (3 * hk + hh) * 128 + 8 * g_;
; #pragma unroll
;             for (int ks = 0; ks < 4; ++ks) qraw[mb][ks] = *(const u32x4*)(qp + 32 * ks);
;         }
;     };
;     if (icnt > 0) { dma_stage(ibase, 1, 0); load_q(ibase, tid & 15, (tid & 63) >> 4); }
.LBB0_302:
	s_ashr_i32 s1, s0, 6
	v_writelane_b32 v255, s74, 7
	s_waitcnt lgkmcnt(0)
	s_add_u32 s20, s6, 0xae00000
	s_addc_u32 s21, s7, 0
	v_writelane_b32 v255, s75, 8
	v_writelane_b32 v255, s84, 9
	s_add_u32 s22, s6, 0x12e00000
	s_load_dwordx4 s[8:11], s[4:5], 0x30
	v_writelane_b32 v255, s85, 10
	s_addc_u32 s23, s7, 0
	v_writelane_b32 v255, s86, 11
	s_add_u32 s24, s6, 0x14e00000
	v_writelane_b32 v255, s87, 12
	s_addc_u32 s25, s7, 0
	v_writelane_b32 v255, s78, 13
	s_cmp_gt_i32 s14, 0
	s_mov_b32 s27, 0
	v_writelane_b32 v255, s79, 14
	s_cselect_b64 s[4:5], -1, 0
	s_cmp_lt_i32 s14, 1
	v_and_b32_e32 v200, 63, v0
	v_writelane_b32 v255, s73, 15
	s_cbranch_scc1 .LBB0_304
	v_mov_b32_e32 v1, v200
	s_lshl_b32 s17, s15, 5
	s_waitcnt vmcnt(3)
	v_ashrrev_i32_e32 v6, 4, v1
	s_lshl_b32 s28, s1, 4
	s_bitcmp1_b32 s1, 2
	s_cbranch_scc1 .Laprio0_skip
	s_setprio 1

; #define LAS __attribute__((address_space(3)))
; __device__ __forceinline__ void attn_phase(const Params& p, LAS unsigned char* lds, int li, int tid, int G, bf16_t* __restrict__ dst, const bf16_t* __restrict__ ZGA) {
;     ...
;     auto dma_stage = [&](int item, int kb, int buf) {
;         int l = tid & 63; asm volatile("" : "+v"(l));
;         const int tb = item >> 2, hk = item & 3, tk = tb * 128 + (kb - 1) * 128;
;         LAS unsigned char* kl = lds + buf * 65536; LAS unsigned char* vl = kl + 32768;
; #pragma unroll
;         for (int i = 0; i < 4; ++i) {
;             const int r = 4 * (4 * w + i) + (l >> 4), c = (l & 15) ^ (r & 15);
;             __builtin_amdgcn_global_load_lds((const unsigned*)(ZK + (size_t)(tk + r) * 512 + hk * 128 + c * 8), (LAS unsigned*)(kl + (4 * w + i) * 1024), 16, 0, 0);
;             __builtin_amdgcn_global_load_lds((const unsigned*)(ZVT + (size_t)(hk * 128 + r) * T + tk + c * 8), (LAS unsigned*)(vl + (4 * w + i) * 1024), 16, 0, 0);
;         }
;     };
;     int buf = 0, curhk = -1;
;     int ibase, istep, icnt;
;     if (G & 7) { ibase = blockIdx.x; istep = G; icnt = ibase < 1024 ? (1024 - ibase + G - 1) / G : 0; }
;     else { const int nper = G >> 3, j0 = blockIdx.x >> 3; ibase = (blockIdx.x & 7) * 128 + j0; istep = nper; icnt = j0 < 128 ? (128 - j0 + nper - 1) / nper : 0; }
;     u32x4 qraw[3][4];
;     auto load_q = [&](int item, int lq_, int g_) {
;         const int tb = item >> 2, hk = item & 3;
; #pragma unroll
;         for (int mb = 0; mb < 3; ++mb) {
;             const int hh = mb, r = 16 * w + lq_;
;             const bf16_t* qp = Z0 + (size_t)(tb * 128 + r) * 2048 + (3 * hk + hh) * 128 + 8 * g_;
; #pragma unroll
;             for (int ks = 0; ks < 4; ++ks) qraw[mb][ks] = *(const u32x4*)(qp + 32 * ks);
;         }
;     };
;     if (icnt > 0) { dma_stage(ibase, 1, 0); load_q(ibase, tid & 15, (tid & 63) >> 4); }
.LBB0_1056:
	s_ashr_i32 s1, s0, 6
	s_waitcnt lgkmcnt(0)
	s_add_u32 s12, s10, 0xae00000
	s_addc_u32 s13, s11, 0
	s_add_u32 s50, s10, 0x12e00000
	s_load_dwordx4 s[16:19], s[8:9], 0x30
	s_addc_u32 s51, s11, 0
	s_add_u32 s52, s10, 0x14e00000
	s_addc_u32 s53, s11, 0
	s_cmp_gt_i32 s21, 0
	s_mov_b32 s29, 0
	s_cselect_b64 s[8:9], -1, 0
	s_cmp_lt_i32 s21, 1
	v_and_b32_e32 v200, 63, v0
	s_cbranch_scc1 .LBB0_1058
	v_mov_b32_e32 v1, v200
	s_lshl_b32 s4, s2, 5
	s_waitcnt vmcnt(3)
	v_ashrrev_i32_e32 v6, 4, v1
	s_lshl_b32 s7, s1, 4
	s_bitcmp1_b32 s1, 2
	s_cbranch_scc1 .Laprio1_skip
	s_setprio 1
